# v92 + s2 row split rebalanced: waves with two HGRN pass-A tasks take 3 rows (was 5), V-transpose waves 8, then 896 waves x 11 and 320 x 10 (was 384 x 11, 832 x 10)
# speedup vs baseline: 1.0046x; 1.0046x over previous
.LBB0_447:
	s_and_b64 vcc, exec, s[0:1]
	s_cbranch_vccz .LBB0_557
	s_movk_i32 s0, 0xff
	v_cmp_lt_i32_e32 vcc, s0, v81
	s_and_saveexec_b64 s[0:1], vcc
	s_xor_b64 s[42:43], exec, s[0:1]
	s_cbranch_execz .LBB0_531
	s_movk_i32 s0, 0x33f
	v_cmp_lt_u32_e32 vcc, s0, v81
	s_and_saveexec_b64 s[0:1], vcc
	s_xor_b64 s[16:17], exec, s[0:1]
	s_cbranch_execz .LBB0_501
	s_movk_i32 s0, 0x6bf
	v_cmp_lt_u32_e32 vcc, s0, v81
	v_readlane_b32 s4, v254, 28
	v_readlane_b32 s0, v255, 7
	v_readlane_b32 s5, v254, 29
	s_add_u32 s2, s4, 0x16f00000
	v_readlane_b32 s1, v255, 8
	s_addc_u32 s3, s5, 0
	s_lshl_b64 s[0:1], s[0:1], 2
	s_add_u32 s0, s4, s0
	s_addc_u32 s1, s5, s1
	s_add_u32 s18, s0, 0x2000
	s_addc_u32 s19, s1, 0
	s_and_saveexec_b64 s[0:1], vcc
	s_xor_b64 s[28:29], exec, s[0:1]
	s_cbranch_execz .LBB0_475
	v_mov_b32_e32 v0, 0xfffff800
	v_mov_b32_e32 v1, -1
	v_mad_u64_u32 v[8:9], s[0:1], v81, 10, v[0:1]
	v_mov_b32_e32 v9, v236
	v_readlane_b32 s4, v255, 11
	v_and_b32_e32 v17, 15, v9
	v_bfe_u32 v19, v9, 4, 2
	v_lshlrev_b32_e32 v21, 2, v17
	v_lshlrev_b32_e32 v12, 6, v19
	v_or_b32_e32 v23, 8, v19
	v_readlane_b32 s5, v255, 12
	v_or_b32_e32 v20, 0x100, v21
	v_min_u32_e32 v0, 9, v23
	v_mov_b64_e32 v[10:11], s[4:5]
	s_movk_i32 s0, 0x1200
	v_or_b32_e32 v22, v12, v21
	v_or_b32_e32 v16, v12, v20
	v_lshlrev_b32_e32 v25, 6, v0
	v_mad_i64_i32 v[10:11], s[0:1], v8, s0, v[10:11]
	v_lshlrev_b32_e32 v160, 1, v22
	v_lshl_add_u64 v[12:13], v[10:11], 0, v[160:161]
	v_lshlrev_b32_e32 v160, 1, v16
	v_or_b32_e32 v24, v25, v21
	v_lshlrev_b32_e32 v4, 4, v17
	v_lshl_add_u64 v[14:15], v[10:11], 0, v[160:161]
	v_lshlrev_b32_e32 v160, 1, v24
	global_load_dwordx4 v[0:3], v4, s[18:19]
	s_nop 0
	global_load_dwordx4 v[4:7], v4, s[18:19] offset:1024
	v_lshl_add_u64 v[10:11], v[10:11], 0, v[160:161]
	global_load_dwordx2 v[46:47], v[12:13], off offset:512
	global_load_dwordx2 v[44:45], v[14:15], off offset:512
	global_load_dwordx2 v[38:39], v[10:11], off offset:512
	v_and_b32_e32 v10, 63, v9
	v_and_b32_e32 v9, 4, v9
	v_cmp_eq_u32_e64 s[36:37], 0, v9
	v_and_b32_e32 v9, 12, v21
	v_cvt_f32_ubyte0_e32 v14, v9
	v_mul_f32_e32 v14, 0xbf549a78, v14
	v_exp_f32_e32 v59, v14
	v_or_b32_e32 v14, 1, v9
	v_cvt_f32_ubyte0_e32 v14, v14
	v_mul_f32_e32 v14, 0xbf549a78, v14
	v_exp_f32_e32 v60, v14
	v_or_b32_e32 v14, 2, v9
	v_or_b32_e32 v9, 3, v9
	v_cvt_f32_ubyte0_e32 v14, v14
	v_cvt_f32_ubyte0_e32 v9, v9
	v_mul_f32_e32 v14, 0xbf549a78, v14
	v_mul_f32_e32 v9, 0xbf549a78, v9
	v_exp_f32_e32 v61, v14
	v_exp_f32_e32 v62, v9
	v_readlane_b32 s0, v254, 28
	v_add_u32_e32 v18, 0x100, v16
	v_or_b32_e32 v20, v25, v20
	v_mov_b32_e32 v64, 0
	v_lshlrev_b32_e32 v160, 3, v10
	v_readlane_b32 s1, v254, 29
	v_cmp_gt_u32_e32 vcc, 10, v23
	v_lshlrev_b32_e64 v58, v19, 1
	v_lshl_add_u64 v[10:11], s[4:5], 0, v[160:161]
	v_cmp_gt_u32_e64 s[38:39], 8, v17
	v_lshl_add_u64 v[12:13], s[2:3], 0, v[160:161]
	v_lshl_add_u64 v[14:15], s[0:1], 0, v[160:161]
	s_mov_b32 s14, 0
	v_lshlrev_b32_e32 v16, 1, v16
	v_lshlrev_b32_e32 v18, 1, v18
	v_lshlrev_b32_e32 v20, 1, v20
	v_lshlrev_b32_e32 v22, 1, v22
	v_lshlrev_b32_e32 v24, 1, v24
	v_mov_b32_e32 v63, v8
	v_mov_b32_e32 v23, 0
	v_mov_b32_e32 v40, 0
	v_mov_b32_e32 v41, v64
	v_mov_b32_e32 v42, 0
	v_mov_b32_e32 v43, v64
	s_branch .LBB0_453

.LBB0_475:
	s_andn2_saveexec_b64 s[28:29], s[28:29]
	s_cbranch_execz .LBB0_500
	v_mov_b32_e32 v0, 0xfffff140
	v_mov_b32_e32 v1, -1
	v_mad_u64_u32 v[8:9], s[0:1], v81, 11, v[0:1]
	v_mov_b32_e32 v9, v236
	v_readlane_b32 s4, v255, 11
	v_and_b32_e32 v17, 15, v9
	v_bfe_u32 v19, v9, 4, 2
	v_lshlrev_b32_e32 v21, 2, v17
	v_lshlrev_b32_e32 v12, 6, v19
	v_or_b32_e32 v23, 8, v19
	v_readlane_b32 s5, v255, 12
	v_or_b32_e32 v20, 0x100, v21
	v_min_u32_e32 v0, 9, v23
	v_mov_b64_e32 v[10:11], s[4:5]
	s_movk_i32 s0, 0x1200
	v_or_b32_e32 v22, v12, v21
	v_or_b32_e32 v16, v12, v20
	v_lshlrev_b32_e32 v25, 6, v0
	v_mad_u64_u32 v[10:11], s[0:1], v8, s0, v[10:11]
	v_lshlrev_b32_e32 v160, 1, v22
	v_lshl_add_u64 v[12:13], v[10:11], 0, v[160:161]
	v_lshlrev_b32_e32 v160, 1, v16
	v_or_b32_e32 v24, v25, v21
	v_lshlrev_b32_e32 v4, 4, v17
	v_lshl_add_u64 v[14:15], v[10:11], 0, v[160:161]
	v_lshlrev_b32_e32 v160, 1, v24
	global_load_dwordx4 v[0:3], v4, s[18:19]
	s_nop 0
	global_load_dwordx4 v[4:7], v4, s[18:19] offset:1024
	v_lshl_add_u64 v[10:11], v[10:11], 0, v[160:161]
	global_load_dwordx2 v[46:47], v[12:13], off offset:512
	global_load_dwordx2 v[44:45], v[14:15], off offset:512
	global_load_dwordx2 v[38:39], v[10:11], off offset:512
	v_and_b32_e32 v10, 63, v9
	v_and_b32_e32 v9, 4, v9
	v_cmp_eq_u32_e64 s[36:37], 0, v9
	v_and_b32_e32 v9, 12, v21
	v_cvt_f32_ubyte0_e32 v14, v9
	v_mul_f32_e32 v14, 0xbf549a78, v14
	v_exp_f32_e32 v59, v14
	v_or_b32_e32 v14, 1, v9
	v_cvt_f32_ubyte0_e32 v14, v14
	v_mul_f32_e32 v14, 0xbf549a78, v14
	v_exp_f32_e32 v60, v14
	v_or_b32_e32 v14, 2, v9
	v_or_b32_e32 v9, 3, v9
	v_cvt_f32_ubyte0_e32 v14, v14
	v_cvt_f32_ubyte0_e32 v9, v9
	v_mul_f32_e32 v14, 0xbf549a78, v14
	v_mul_f32_e32 v9, 0xbf549a78, v9
	v_exp_f32_e32 v61, v14
	v_exp_f32_e32 v62, v9
	v_readlane_b32 s0, v254, 28
	v_add_u32_e32 v18, 0x100, v16
	v_or_b32_e32 v20, v25, v20
	v_mov_b32_e32 v64, 0
	v_lshlrev_b32_e32 v160, 3, v10
	v_readlane_b32 s1, v254, 29
	v_cmp_gt_u32_e32 vcc, 10, v23
	v_lshlrev_b32_e64 v58, v19, 1
	v_lshl_add_u64 v[10:11], s[4:5], 0, v[160:161]
	v_cmp_gt_u32_e64 s[38:39], 8, v17
	v_lshl_add_u64 v[12:13], s[2:3], 0, v[160:161]
	v_lshl_add_u64 v[14:15], s[0:1], 0, v[160:161]
	s_mov_b32 s10, 0
	v_lshlrev_b32_e32 v16, 1, v16
	v_lshlrev_b32_e32 v18, 1, v18
	v_lshlrev_b32_e32 v20, 1, v20
	v_lshlrev_b32_e32 v22, 1, v22
	v_lshlrev_b32_e32 v24, 1, v24
	v_mov_b32_e32 v63, v8
	v_mov_b32_e32 v23, 0
	v_mov_b32_e32 v40, 0
	v_mov_b32_e32 v41, v64
	v_mov_b32_e32 v42, 0
	v_mov_b32_e32 v43, v64
	s_branch .LBB0_478

.LBB0_501:
	s_andn2_saveexec_b64 s[2:3], s[16:17]
	s_cbranch_execz .LBB0_530
	v_add_u32_e32 v4, 0xffffff00, v81
	s_mov_b32 s0, 0xe38f
	v_mul_u32_u24_sdwa v1, v4, s0 dst_sel:DWORD dst_unused:UNUSED_PAD src0_sel:WORD_0 src1_sel:DWORD
	v_lshrrev_b32_e32 v2, 21, v1
	v_mul_lo_u16_e32 v3, 36, v2
	v_sub_u16_e32 v3, v4, v3
	v_mov_b32_e32 v0, v236
	v_lshrrev_b32_e32 v5, 22, v1
	v_cmp_lt_u16_e32 vcc, 31, v3
	v_lshlrev_b16_e32 v3, 6, v3
	s_and_saveexec_b64 s[0:1], vcc
	s_xor_b64 s[0:1], exec, s[0:1]
	v_lshlrev_b32_e32 v1, 8, v5
	s_movk_i32 s4, 0x3800
	v_add3_u32 v1, v3, v1, s4
	s_andn2_saveexec_b64 s[0:1], s[0:1]
	v_lshl_or_b32 v1, v5, 11, v3
	s_or_b64 exec, exec, s[0:1]
	v_readlane_b32 s8, v254, 28
	v_readlane_b32 s9, v254, 29
	s_movk_i32 s6, 0x1200
	v_lshlrev_b32_e32 v8, 7, v2
	v_mov_b64_e32 v[6:7], s[8:9]
	v_and_b32_e32 v5, 63, v0
	v_mad_u64_u32 v[0:1], s[0:1], v1, s6, v[6:7]
	v_and_b32_e32 v160, 0x80, v8
	v_lshl_add_u64 v[0:1], v[0:1], 0, v[160:161]
	v_lshlrev_b32_e32 v160, 1, v5
	v_lshl_add_u64 v[0:1], v[0:1], 0, v[160:161]
	s_mov_b32 s0, 0xb200000
	v_add_co_u32_e32 v8, vcc, s0, v0
	s_mov_b32 s0, 0xb201000
	s_nop 0
	v_addc_co_u32_e32 v9, vcc, 0, v1, vcc
	v_add_co_u32_e32 v10, vcc, s0, v0
	s_mov_b32 s0, 0xb202000
	s_nop 0
	v_addc_co_u32_e32 v11, vcc, 0, v1, vcc
	v_add_co_u32_e32 v12, vcc, s0, v0
	s_mov_b32 s0, 0xb203000
	s_nop 0
	v_addc_co_u32_e32 v13, vcc, 0, v1, vcc
	v_add_co_u32_e32 v14, vcc, s0, v0
	s_mov_b32 s0, 0xb204000
	s_nop 0
	v_addc_co_u32_e32 v15, vcc, 0, v1, vcc
	v_add_co_u32_e32 v16, vcc, s0, v0
	s_mov_b32 s0, 0xb206000
	s_nop 0
	v_addc_co_u32_e32 v17, vcc, 0, v1, vcc
	v_add_co_u32_e32 v18, vcc, s0, v0
	s_mov_b32 s0, 0xb207000
	s_nop 0
	v_addc_co_u32_e32 v19, vcc, 0, v1, vcc
	v_add_co_u32_e32 v20, vcc, s0, v0
	s_mov_b32 s0, 0xb208000
	s_nop 0
	v_addc_co_u32_e32 v21, vcc, 0, v1, vcc
	v_add_co_u32_e32 v22, vcc, s0, v0
	v_lshl_or_b32 v2, v2, 6, v5
	s_nop 0
	v_addc_co_u32_e32 v23, vcc, 0, v1, vcc
	global_load_ushort v8, v[8:9], off offset:1792
	s_nop 0
	global_load_ushort v9, v[10:11], off offset:2304
	global_load_ushort v24, v[12:13], off offset:2816
	global_load_ushort v25, v[14:15], off offset:3328
	global_load_ushort v26, v[16:17], off offset:3840
	global_load_ushort v27, v[18:19], off offset:256
	global_load_ushort v28, v[20:21], off offset:768
	global_load_ushort v29, v[22:23], off offset:1280
	v_mad_u64_u32 v[6:7], s[0:1], v2, s6, v[6:7]
	s_mov_b32 s0, 0xb209000
	s_nop 0
	v_add_co_u32_e32 v10, vcc, s0, v0
	s_mov_b32 s0, 0xb20a000
	s_nop 0
	v_addc_co_u32_e32 v11, vcc, 0, v1, vcc
	v_add_co_u32_e32 v12, vcc, s0, v0
	s_mov_b32 s0, 0xb20b000
	s_nop 0
	v_addc_co_u32_e32 v13, vcc, 0, v1, vcc
	v_add_co_u32_e32 v14, vcc, s0, v0
	s_mov_b32 s0, 0xb20c000
	s_nop 0
	v_addc_co_u32_e32 v15, vcc, 0, v1, vcc
	v_add_co_u32_e32 v16, vcc, s0, v0
	s_mov_b32 s0, 0xb20d000
	s_nop 0
	v_addc_co_u32_e32 v17, vcc, 0, v1, vcc
	v_add_co_u32_e32 v18, vcc, s0, v0
	s_mov_b32 s0, 0xb20f000
	s_nop 0
	v_addc_co_u32_e32 v19, vcc, 0, v1, vcc
	v_lshlrev_b32_e32 v160, 1, v3
	v_add_co_u32_e32 v20, vcc, s0, v0
	v_lshl_add_u64 v[2:3], v[6:7], 0, v[160:161]
	s_nop 0
	v_addc_co_u32_e32 v21, vcc, 0, v1, vcc
	s_mov_b32 s0, 0x19300000
	v_add_co_u32_e32 v22, vcc, s0, v2
	s_mov_b32 s0, 0xb210000
	s_nop 0
	v_addc_co_u32_e32 v23, vcc, 0, v3, vcc
	v_readlane_b32 s10, v255, 11
	v_readlane_b32 s11, v255, 12
	v_mov_b32_e32 v60, 0
	s_mov_b32 s14, 0
	v_mov_b32_e32 v38, 0
	v_mov_b32_e32 v39, v60
	v_mov_b32_e32 v36, 0
	v_mov_b32_e32 v37, v60
	s_waitcnt vmcnt(0)
	v_lshl_or_b32 v6, v9, 16, v8
	v_lshl_or_b32 v7, v25, 16, v24
	v_lshl_or_b32 v8, v27, 16, v26
	v_lshl_or_b32 v9, v29, 16, v28
	global_store_dwordx4 v[22:23], v[6:9], off
	s_nop 1
	v_add_co_u32_e32 v6, vcc, s0, v0
	s_mov_b32 s0, 0xb211000
	s_nop 0
	v_addc_co_u32_e32 v7, vcc, 0, v1, vcc
	v_add_co_u32_e32 v8, vcc, s0, v0
	s_mov_b32 s0, 0xb212000
	s_nop 0
	v_addc_co_u32_e32 v9, vcc, 0, v1, vcc
	global_load_ushort v5, v[10:11], off offset:1792
	global_load_ushort v26, v[12:13], off offset:2304
	global_load_ushort v27, v[14:15], off offset:2816
	global_load_ushort v28, v[16:17], off offset:3328
	global_load_ushort v29, v[18:19], off offset:3840
	global_load_ushort v30, v[20:21], off offset:256
	global_load_ushort v31, v[6:7], off offset:768
	s_nop 0
	global_load_ushort v9, v[8:9], off offset:1280
	v_add_co_u32_e32 v10, vcc, s0, v0
	s_mov_b32 s0, 0xb213000
	s_nop 0
	v_addc_co_u32_e32 v11, vcc, 0, v1, vcc
	v_add_co_u32_e32 v12, vcc, s0, v0
	s_mov_b32 s0, 0xb214000
	s_nop 0
	v_addc_co_u32_e32 v13, vcc, 0, v1, vcc
	v_add_co_u32_e32 v14, vcc, s0, v0
	s_mov_b32 s0, 0xb215000
	s_nop 0
	v_addc_co_u32_e32 v15, vcc, 0, v1, vcc
	v_add_co_u32_e32 v16, vcc, s0, v0
	s_mov_b32 s0, 0xb216000
	s_nop 0
	v_addc_co_u32_e32 v17, vcc, 0, v1, vcc
	v_add_co_u32_e32 v18, vcc, s0, v0
	s_mov_b32 s0, 0xb218000
	s_nop 0
	v_addc_co_u32_e32 v19, vcc, 0, v1, vcc
	v_add_co_u32_e32 v20, vcc, s0, v0
	s_mov_b32 s0, 0xb219000
	s_nop 0
	v_addc_co_u32_e32 v21, vcc, 0, v1, vcc
	v_add_co_u32_e32 v22, vcc, s0, v0
	s_mov_b32 s0, 0xb21a000
	s_nop 0
	v_addc_co_u32_e32 v23, vcc, 0, v1, vcc
	v_add_co_u32_e32 v24, vcc, s0, v0
	s_mov_b64 s[0:1], 0x19300000
	v_lshl_add_u64 v[2:3], v[2:3], 0, s[0:1]
	v_addc_co_u32_e32 v25, vcc, 0, v1, vcc
	s_mov_b32 s0, 0xb21b000
	s_waitcnt vmcnt(0)
	v_lshl_or_b32 v6, v26, 16, v5
	v_lshl_or_b32 v7, v28, 16, v27
	v_lshl_or_b32 v8, v30, 16, v29
	v_lshl_or_b32 v9, v9, 16, v31
	global_store_dwordx4 v[2:3], v[6:9], off offset:16
	global_load_ushort v5, v[10:11], off offset:1792
	s_nop 0
	global_load_ushort v6, v[12:13], off offset:2304
	global_load_ushort v7, v[14:15], off offset:2816
	global_load_ushort v8, v[16:17], off offset:3328
	global_load_ushort v9, v[18:19], off offset:3840
	global_load_ushort v26, v[20:21], off offset:256
	global_load_ushort v27, v[22:23], off offset:768
	global_load_ushort v28, v[24:25], off offset:1280
	v_add_co_u32_e32 v10, vcc, s0, v0
	s_mov_b32 s0, 0xb21c000
	s_nop 0
	v_addc_co_u32_e32 v11, vcc, 0, v1, vcc
	v_add_co_u32_e32 v12, vcc, s0, v0
	s_mov_b32 s0, 0xb21d000
	s_nop 0
	v_addc_co_u32_e32 v13, vcc, 0, v1, vcc
	v_add_co_u32_e32 v14, vcc, s0, v0
	s_mov_b32 s0, 0xb21e000
	s_nop 0
	v_addc_co_u32_e32 v15, vcc, 0, v1, vcc
	v_add_co_u32_e32 v16, vcc, s0, v0
	s_mov_b32 s0, 0xb21f000
	s_nop 0
	v_addc_co_u32_e32 v17, vcc, 0, v1, vcc
	v_add_co_u32_e32 v18, vcc, s0, v0
	s_mov_b32 s0, 0xb221000
	s_nop 0
	v_addc_co_u32_e32 v19, vcc, 0, v1, vcc
	v_add_co_u32_e32 v20, vcc, s0, v0
	s_mov_b32 s0, 0xb222000
	s_nop 0
	v_addc_co_u32_e32 v21, vcc, 0, v1, vcc
	v_add_co_u32_e32 v22, vcc, s0, v0
	s_mov_b32 s0, 0xb223000
	s_nop 0
	v_addc_co_u32_e32 v23, vcc, 0, v1, vcc
	v_add_co_u32_e32 v24, vcc, s0, v0
	s_mov_b32 s0, 0xb224000
	s_nop 0
	v_addc_co_u32_e32 v25, vcc, 0, v1, vcc
	s_waitcnt vmcnt(0)
	v_lshl_or_b32 v6, v6, 16, v5
	v_lshl_or_b32 v7, v8, 16, v7
	v_lshl_or_b32 v8, v26, 16, v9
	v_lshl_or_b32 v9, v28, 16, v27
	global_store_dwordx4 v[2:3], v[6:9], off offset:32
	global_load_ushort v5, v[10:11], off offset:1792
	s_nop 0
	global_load_ushort v6, v[12:13], off offset:2304
	global_load_ushort v7, v[14:15], off offset:2816
	global_load_ushort v8, v[16:17], off offset:3328
	global_load_ushort v9, v[18:19], off offset:3840
	global_load_ushort v26, v[20:21], off offset:256
	global_load_ushort v27, v[22:23], off offset:768
	global_load_ushort v28, v[24:25], off offset:1280
	v_add_co_u32_e32 v10, vcc, s0, v0
	s_mov_b32 s0, 0xb225000
	s_nop 0
	v_addc_co_u32_e32 v11, vcc, 0, v1, vcc
	v_add_co_u32_e32 v12, vcc, s0, v0
	s_mov_b32 s0, 0xb226000
	s_nop 0
	v_addc_co_u32_e32 v13, vcc, 0, v1, vcc
	v_add_co_u32_e32 v14, vcc, s0, v0
	s_mov_b32 s0, 0xb227000
	s_nop 0
	v_addc_co_u32_e32 v15, vcc, 0, v1, vcc
	v_add_co_u32_e32 v16, vcc, s0, v0
	s_mov_b32 s0, 0xb228000
	s_nop 0
	v_addc_co_u32_e32 v17, vcc, 0, v1, vcc
	v_add_co_u32_e32 v18, vcc, s0, v0
	s_mov_b32 s0, 0xb22a000
	s_nop 0
	v_addc_co_u32_e32 v19, vcc, 0, v1, vcc
	v_add_co_u32_e32 v20, vcc, s0, v0
	s_mov_b32 s0, 0xb22b000
	s_nop 0
	v_addc_co_u32_e32 v21, vcc, 0, v1, vcc
	v_add_co_u32_e32 v22, vcc, s0, v0
	s_mov_b32 s0, 0xb22c000
	s_nop 0
	v_addc_co_u32_e32 v23, vcc, 0, v1, vcc
	v_add_co_u32_e32 v24, vcc, s0, v0
	s_mov_b32 s0, 0xb22d000
	s_nop 0
	v_addc_co_u32_e32 v25, vcc, 0, v1, vcc
	s_waitcnt vmcnt(0)
	v_lshl_or_b32 v6, v6, 16, v5
	v_lshl_or_b32 v7, v8, 16, v7
	v_lshl_or_b32 v8, v26, 16, v9
	v_lshl_or_b32 v9, v28, 16, v27
	global_store_dwordx4 v[2:3], v[6:9], off offset:48
	global_load_ushort v5, v[10:11], off offset:1792
	s_nop 0
	global_load_ushort v6, v[12:13], off offset:2304
	global_load_ushort v7, v[14:15], off offset:2816
	global_load_ushort v8, v[16:17], off offset:3328
	global_load_ushort v9, v[18:19], off offset:3840
	global_load_ushort v26, v[20:21], off offset:256
	global_load_ushort v27, v[22:23], off offset:768
	global_load_ushort v28, v[24:25], off offset:1280
	v_add_co_u32_e32 v10, vcc, s0, v0
	s_mov_b32 s0, 0xb22e000
	s_nop 0
	v_addc_co_u32_e32 v11, vcc, 0, v1, vcc
	v_add_co_u32_e32 v12, vcc, s0, v0
	s_mov_b32 s0, 0xb22f000
	s_nop 0
	v_addc_co_u32_e32 v13, vcc, 0, v1, vcc
	v_add_co_u32_e32 v14, vcc, s0, v0
	s_mov_b32 s0, 0xb230000
	s_nop 0
	v_addc_co_u32_e32 v15, vcc, 0, v1, vcc
	v_add_co_u32_e32 v16, vcc, s0, v0
	s_mov_b32 s0, 0xb231000
	s_nop 0
	v_addc_co_u32_e32 v17, vcc, 0, v1, vcc
	v_add_co_u32_e32 v18, vcc, s0, v0
	s_mov_b32 s0, 0xb233000
	s_nop 0
	v_addc_co_u32_e32 v19, vcc, 0, v1, vcc
	v_add_co_u32_e32 v20, vcc, s0, v0
	s_mov_b32 s0, 0xb234000
	s_nop 0
	v_addc_co_u32_e32 v21, vcc, 0, v1, vcc
	v_add_co_u32_e32 v22, vcc, s0, v0
	s_mov_b32 s0, 0xb235000
	s_nop 0
	v_addc_co_u32_e32 v23, vcc, 0, v1, vcc
	v_add_co_u32_e32 v24, vcc, s0, v0
	s_mov_b32 s0, 0xb236000
	s_nop 0
	v_addc_co_u32_e32 v25, vcc, 0, v1, vcc
	s_waitcnt vmcnt(0)
	v_lshl_or_b32 v6, v6, 16, v5
	v_lshl_or_b32 v7, v8, 16, v7
	v_lshl_or_b32 v8, v26, 16, v9
	v_lshl_or_b32 v9, v28, 16, v27
	global_store_dwordx4 v[2:3], v[6:9], off offset:64
	global_load_ushort v5, v[10:11], off offset:1792
	s_nop 0
	global_load_ushort v6, v[12:13], off offset:2304
	global_load_ushort v7, v[14:15], off offset:2816
	global_load_ushort v8, v[16:17], off offset:3328
	global_load_ushort v9, v[18:19], off offset:3840
	global_load_ushort v26, v[20:21], off offset:256
	global_load_ushort v27, v[22:23], off offset:768
	global_load_ushort v28, v[24:25], off offset:1280
	v_add_co_u32_e32 v10, vcc, s0, v0
	s_mov_b32 s0, 0xb237000
	s_nop 0
	v_addc_co_u32_e32 v11, vcc, 0, v1, vcc
	v_add_co_u32_e32 v12, vcc, s0, v0
	s_mov_b32 s0, 0xb238000
	s_nop 0
	v_addc_co_u32_e32 v13, vcc, 0, v1, vcc
	v_add_co_u32_e32 v14, vcc, s0, v0
	s_mov_b32 s0, 0xb239000
	s_nop 0
	v_addc_co_u32_e32 v15, vcc, 0, v1, vcc
	v_add_co_u32_e32 v16, vcc, s0, v0
	s_mov_b32 s0, 0xb23a000
	s_nop 0
	v_addc_co_u32_e32 v17, vcc, 0, v1, vcc
	v_add_co_u32_e32 v18, vcc, s0, v0
	s_mov_b32 s0, 0xb23c000
	s_nop 0
	v_addc_co_u32_e32 v19, vcc, 0, v1, vcc
	v_add_co_u32_e32 v20, vcc, s0, v0
	s_mov_b32 s0, 0xb23d000
	s_nop 0
	v_addc_co_u32_e32 v21, vcc, 0, v1, vcc
	v_add_co_u32_e32 v22, vcc, s0, v0
	s_mov_b32 s0, 0xb23e000
	s_nop 0
	v_addc_co_u32_e32 v23, vcc, 0, v1, vcc
	v_add_co_u32_e32 v24, vcc, s0, v0
	s_mov_b32 s0, 0xb23f000
	s_nop 0
	v_addc_co_u32_e32 v25, vcc, 0, v1, vcc
	s_waitcnt vmcnt(0)
	v_lshl_or_b32 v6, v6, 16, v5
	v_lshl_or_b32 v7, v8, 16, v7
	v_lshl_or_b32 v8, v26, 16, v9
	v_lshl_or_b32 v9, v28, 16, v27
	global_store_dwordx4 v[2:3], v[6:9], off offset:80
	global_load_ushort v5, v[10:11], off offset:1792
	s_nop 0
	global_load_ushort v6, v[12:13], off offset:2304
	global_load_ushort v7, v[14:15], off offset:2816
	global_load_ushort v8, v[16:17], off offset:3328
	global_load_ushort v9, v[18:19], off offset:3840
	global_load_ushort v26, v[20:21], off offset:256
	global_load_ushort v27, v[22:23], off offset:768
	s_nop 0
	global_load_ushort v24, v[24:25], off offset:1280
	v_add_co_u32_e32 v10, vcc, s0, v0
	s_mov_b32 s0, 0xb240000
	s_nop 0
	v_addc_co_u32_e32 v11, vcc, 0, v1, vcc
	v_add_co_u32_e32 v12, vcc, s0, v0
	s_mov_b32 s0, 0xb241000
	s_nop 0
	v_addc_co_u32_e32 v13, vcc, 0, v1, vcc
	v_add_co_u32_e32 v14, vcc, s0, v0
	s_mov_b32 s0, 0xb242000
	s_nop 0
	v_addc_co_u32_e32 v15, vcc, 0, v1, vcc
	v_add_co_u32_e32 v16, vcc, s0, v0
	s_mov_b32 s0, 0xb243000
	s_nop 0
	v_addc_co_u32_e32 v17, vcc, 0, v1, vcc
	v_add_co_u32_e32 v18, vcc, s0, v0
	s_mov_b32 s0, 0xb245000
	s_nop 0
	v_addc_co_u32_e32 v19, vcc, 0, v1, vcc
	v_add_co_u32_e32 v20, vcc, s0, v0
	s_mov_b32 s0, 0xb246000
	s_nop 0
	v_addc_co_u32_e32 v21, vcc, 0, v1, vcc
	v_add_co_u32_e32 v22, vcc, s0, v0
	s_mov_b32 s0, 0xb247000
	s_nop 0
	v_addc_co_u32_e32 v23, vcc, 0, v1, vcc
	v_add_co_u32_e32 v0, vcc, s0, v0
	v_readlane_b32 s0, v255, 7
	s_nop 0
	v_addc_co_u32_e32 v1, vcc, 0, v1, vcc
	v_readlane_b32 s1, v255, 8
	s_lshl_b64 s[0:1], s[0:1], 2
	s_add_u32 s0, s8, s0
	s_addc_u32 s1, s9, s1
	s_waitcnt vmcnt(0)
	v_lshl_or_b32 v6, v6, 16, v5
	v_lshl_or_b32 v7, v8, 16, v7
	v_lshl_or_b32 v8, v26, 16, v9
	v_lshl_or_b32 v9, v24, 16, v27
	global_store_dwordx4 v[2:3], v[6:9], off offset:96
	global_load_ushort v5, v[10:11], off offset:1792
	s_nop 0
	global_load_ushort v6, v[12:13], off offset:2304
	global_load_ushort v7, v[14:15], off offset:2816
	global_load_ushort v10, v[16:17], off offset:3328
	global_load_ushort v11, v[18:19], off offset:3840
	s_nop 0
	global_load_ushort v12, v[20:21], off offset:256
	global_load_ushort v13, v[22:23], off offset:768
	global_load_ushort v14, v[0:1], off offset:1280
	v_mov_b32_e32 v0, 0x300
	v_lshl_add_u32 v54, v4, 3, v0
	v_mov_b32_e32 v15, v236
	v_mov_b64_e32 v[0:1], s[10:11]
	v_mad_u64_u32 v[8:9], s[4:5], v54, s6, v[0:1]
	s_waitcnt vmcnt(0)
	v_lshl_or_b32 v4, v6, 16, v5
	v_lshl_or_b32 v5, v10, 16, v7
	v_lshl_or_b32 v6, v12, 16, v11
	v_lshl_or_b32 v7, v14, 16, v13
	global_store_dwordx4 v[2:3], v[4:7], off offset:112
	s_nop 0
	v_and_b32_e32 v14, 15, v15
	v_bfe_u32 v17, v15, 4, 2
	v_lshlrev_b32_e32 v19, 2, v14
	v_lshlrev_b32_e32 v2, 6, v17
	v_or_b32_e32 v21, 8, v17
	v_lshlrev_b32_e32 v160, 4, v14
	v_or_b32_e32 v23, 0x100, v19
	v_min_u32_e32 v3, 9, v21
	v_or_b32_e32 v20, v2, v19
	v_lshl_add_u64 v[0:1], s[0:1], 0, v[160:161]
	v_or_b32_e32 v16, v2, v23
	v_lshlrev_b32_e32 v24, 6, v3
	s_mov_b64 s[0:1], 0x2000
	v_lshlrev_b32_e32 v160, 1, v20
	v_lshl_add_u64 v[4:5], v[0:1], 0, s[0:1]
	v_add_co_u32_e32 v0, vcc, s20, v0
	v_lshl_add_u64 v[10:11], v[8:9], 0, v[160:161]
	v_lshlrev_b32_e32 v160, 1, v16
	v_or_b32_e32 v22, v24, v19
	v_addc_co_u32_e32 v1, vcc, 0, v1, vcc
	v_lshl_add_u64 v[12:13], v[8:9], 0, v[160:161]
	v_lshlrev_b32_e32 v160, 1, v22
	global_load_dwordx4 v[0:3], v[0:1], off
	s_nop 0
	global_load_dwordx4 v[4:7], v[4:5], off offset:1024
	v_lshl_add_u64 v[8:9], v[8:9], 0, v[160:161]
	global_load_dwordx2 v[42:43], v[10:11], off offset:512
	global_load_dwordx2 v[40:41], v[12:13], off offset:512
	global_load_dwordx2 v[34:35], v[8:9], off offset:512
	v_and_b32_e32 v8, 63, v15
	v_and_b32_e32 v9, 4, v15
	v_lshlrev_b32_e32 v160, 3, v8
	v_cmp_eq_u32_e64 s[36:37], 0, v9
	v_cmp_gt_u32_e64 s[38:39], 8, v14
	v_and_b32_e32 v14, 12, v19
	v_lshl_add_u64 v[8:9], s[8:9], 0, v[160:161]
	s_mov_b64 s[0:1], 0x16f00000
	v_lshl_add_u64 v[12:13], v[8:9], 0, s[0:1]
	v_cvt_f32_ubyte0_e32 v8, v14
	v_mul_f32_e32 v8, 0xbf549a78, v8
	v_exp_f32_e32 v56, v8
	v_or_b32_e32 v8, 1, v14
	v_cvt_f32_ubyte0_e32 v8, v8
	v_mul_f32_e32 v8, 0xbf549a78, v8
	v_exp_f32_e32 v57, v8
	v_or_b32_e32 v8, 2, v14
	v_cvt_f32_ubyte0_e32 v8, v8
	v_mul_f32_e32 v8, 0xbf549a78, v8
	v_exp_f32_e32 v58, v8
	v_or_b32_e32 v8, 3, v14
	v_cvt_f32_ubyte0_e32 v8, v8
	v_mul_f32_e32 v8, 0xbf549a78, v8
	v_exp_f32_e32 v59, v8
	v_mad_i64_i32 v[8:9], s[0:1], v54, s6, 0
	v_add_u32_e32 v18, 0x100, v16
	v_or_b32_e32 v24, v24, v23
	v_or_b32_e32 v8, v8, v160
	v_cmp_gt_u32_e32 vcc, 10, v21
	v_lshlrev_b32_e64 v55, v17, 1
	v_lshl_add_u64 v[10:11], s[10:11], 0, v[160:161]
	v_lshl_add_u64 v[14:15], s[10:11], 0, v[8:9]
	v_lshlrev_b32_e32 v8, 1, v16
	v_lshlrev_b32_e32 v16, 1, v18
	v_lshlrev_b32_e32 v18, 1, v24
	v_lshlrev_b32_e32 v20, 1, v20
	v_lshlrev_b32_e32 v22, 1, v22
	v_mov_b32_e32 v21, 0
	s_branch .LBB0_508

.LBB0_531:
	s_andn2_saveexec_b64 s[2:3], s[42:43]
	s_cbranch_execz .LBB0_556
	v_readlane_b32 s0, v255, 7
	v_mov_b32_e32 v9, v236
	v_readlane_b32 s1, v255, 8
	s_lshl_b64 s[0:1], s[0:1], 2
	v_bfe_u32 v19, v9, 4, 2
	v_readlane_b32 s4, v254, 28
	v_and_b32_e32 v17, 15, v9
	v_or_b32_e32 v23, 8, v19
	v_readlane_b32 s5, v254, 29
	s_add_u32 s0, s4, s0
	v_min_u32_e32 v0, 9, v23
	s_addc_u32 s1, s5, s1
	v_lshlrev_b32_e32 v160, 4, v17
	v_readlane_b32 s6, v255, 11
	v_lshlrev_b32_e32 v21, 2, v17
	v_lshlrev_b32_e32 v12, 6, v19
	v_lshlrev_b32_e32 v24, 6, v0
	v_lshl_add_u64 v[0:1], s[0:1], 0, v[160:161]
	s_mov_b64 s[0:1], 0x2000
	v_readlane_b32 s7, v255, 12
	v_lshl_add_u32 v56, v81, 1, v81
	v_or_b32_e32 v18, 0x100, v21
	v_lshl_add_u64 v[4:5], v[0:1], 0, s[0:1]
	v_mov_b64_e32 v[10:11], s[6:7]
	s_movk_i32 s0, 0x1200
	v_or_b32_e32 v20, v12, v21
	v_or_b32_e32 v8, v12, v18
	v_mad_i64_i32 v[10:11], s[0:1], v56, s0, v[10:11]
	v_lshlrev_b32_e32 v160, 1, v20
	v_add_co_u32_e32 v0, vcc, s20, v0
	v_lshl_add_u64 v[12:13], v[10:11], 0, v[160:161]
	v_lshlrev_b32_e32 v160, 1, v8
	v_or_b32_e32 v22, v24, v21
	v_addc_co_u32_e32 v1, vcc, 0, v1, vcc
	v_lshl_add_u64 v[14:15], v[10:11], 0, v[160:161]
	v_lshlrev_b32_e32 v160, 1, v22
	global_load_dwordx4 v[0:3], v[0:1], off
	s_nop 0
	global_load_dwordx4 v[4:7], v[4:5], off offset:1024
	v_lshl_add_u64 v[10:11], v[10:11], 0, v[160:161]
	global_load_dwordx2 v[44:45], v[12:13], off offset:512
	global_load_dwordx2 v[42:43], v[14:15], off offset:512
	global_load_dwordx2 v[36:37], v[10:11], off offset:512
	v_and_b32_e32 v10, 63, v9
	v_and_b32_e32 v9, 4, v9
	v_cmp_eq_u32_e64 s[36:37], 0, v9
	v_and_b32_e32 v9, 12, v21
	v_cmp_gt_u32_e64 s[38:39], 8, v17
	v_cvt_f32_ubyte0_e32 v17, v9
	v_mul_f32_e32 v17, 0xbf549a78, v17
	v_exp_f32_e32 v58, v17
	v_or_b32_e32 v17, 1, v9
	v_cvt_f32_ubyte0_e32 v17, v17
	v_mul_f32_e32 v17, 0xbf549a78, v17
	v_exp_f32_e32 v59, v17
	v_or_b32_e32 v17, 2, v9
	v_or_b32_e32 v9, 3, v9
	v_cvt_f32_ubyte0_e32 v17, v17
	v_cvt_f32_ubyte0_e32 v9, v9
	v_mul_f32_e32 v17, 0xbf549a78, v17
	v_mul_f32_e32 v9, 0xbf549a78, v9
	v_exp_f32_e32 v60, v17
	v_exp_f32_e32 v61, v9
	v_lshlrev_b32_e32 v160, 3, v10
	v_add_u32_e32 v16, 0x100, v8
	v_or_b32_e32 v18, v24, v18
	v_mov_b32_e32 v63, 0
	v_lshl_add_u64 v[12:13], s[4:5], 0, v[160:161]
	s_mov_b64 s[0:1], 0x16f00000
	v_cmp_gt_u32_e32 vcc, 10, v23
	v_lshlrev_b32_e64 v57, v19, 1
	v_lshl_add_u64 v[10:11], s[6:7], 0, v[160:161]
	v_lshl_add_u64 v[14:15], v[12:13], 0, s[0:1]
	s_mov_b32 s14, 0
	v_lshlrev_b32_e32 v8, 1, v8
	v_lshlrev_b32_e32 v16, 1, v16
	v_lshlrev_b32_e32 v18, 1, v18
	v_lshlrev_b32_e32 v20, 1, v20
	v_lshlrev_b32_e32 v22, 1, v22
	v_mov_b32_e32 v62, v56
	v_mov_b32_e32 v21, 0
	v_mov_b32_e32 v38, 0
	v_mov_b32_e32 v39, v63
	v_mov_b32_e32 v40, 0
	v_mov_b32_e32 v41, v63
	s_branch .LBB0_534
.LBB0_533:
	s_or_b64 exec, exec, s[0:1]
	v_sub_u32_e32 v9, v17, v63
	v_cvt_f32_i32_e32 v9, v9
	s_waitcnt vmcnt(2)
	v_lshlrev_b32_e32 v200, 16, v196
	v_and_b32_e32 v201, 0xffff0000, v196
	v_lshlrev_b32_e32 v202, 16, v198
	v_and_b32_e32 v203, 0xffff0000, v198
	v_pk_add_f32 v[200:201], v[200:201], v[202:203] neg_lo:[0,1] neg_hi:[0,1]
	v_lshlrev_b32_e32 v198, 16, v199
	v_pk_add_f32 v[40:41], v[40:41], v[200:201]
	v_lshlrev_b32_e32 v200, 16, v197
	v_and_b32_e32 v201, 0xffff0000, v197
	v_and_b32_e32 v199, 0xffff0000, v199
	v_pk_add_f32 v[200:201], v[200:201], v[198:199] neg_lo:[0,1] neg_hi:[0,1]
	s_nop 0
	v_pk_add_f32 v[38:39], v[38:39], v[200:201]
	v_lshlrev_b32_e32 v36, 16, v34
	v_and_b32_e32 v37, 0xffff0000, v34
	s_add_i32 s14, s14, 1
	v_rcp_iflag_f32_e32 v32, v9
	v_lshlrev_b64 v[24:25], 11, v[24:25]
	v_lshl_add_u64 v[24:25], v[14:15], 0, v[24:25]
	v_add_u32_e32 v62, 1, v62
	v_pk_fma_f32 v[36:37], v[32:33], v[40:41], v[36:37] op_sel_hi:[0,1,1] neg_lo:[0,0,1] neg_hi:[0,0,1]
	v_cvt_pk_bf16_f32 v34, v36, v37
	v_lshlrev_b32_e32 v36, 16, v35
	v_and_b32_e32 v37, 0xffff0000, v35
	v_pk_fma_f32 v[32:33], v[32:33], v[38:39], v[36:37] op_sel_hi:[0,1,1] neg_lo:[0,0,1] neg_hi:[0,0,1]
	v_cvt_pk_bf16_f32 v35, v32, v33
	s_cmp_eq_u32 s14, 3
	v_mov_b32_e32 v21, v17
	v_mov_b32_e32 v44, v26
	v_mov_b32_e32 v45, v27
	v_mov_b32_e32 v42, v28
	v_mov_b32_e32 v43, v29
	v_mov_b32_e32 v36, v30
	v_mov_b32_e32 v37, v31
	global_store_dwordx2 v[24:25], v[34:35], off
	s_cbranch_scc1 .LBB0_556
.LBB0_534:
	v_readlane_b32 s0, v255, 11
	v_readlane_b32 s1, v255, 12
	v_add_u32_e32 v24, s14, v56
	s_cmp_gt_u32 s14, 1
	v_mov_b64_e32 v[26:27], s[0:1]
	s_movk_i32 s0, 0x1200
	v_mad_i64_i32 v[32:33], s[0:1], v24, s0, v[26:27]
	s_waitcnt vmcnt(0)
	v_mov_b32_e32 v26, v44
	v_mov_b32_e32 v27, v45
	v_mov_b32_e32 v28, v42
	v_mov_b32_e32 v29, v43
	v_mov_b32_e32 v30, v36
	v_mov_b32_e32 v31, v37
	s_cbranch_scc1 .LBB0_536
	v_lshl_add_u64 v[26:27], v[32:33], 0, s[34:35]
	v_mov_b32_e32 v9, v161
	v_mov_b32_e32 v17, v161
	v_lshl_add_u64 v[28:29], v[26:27], 0, v[8:9]
	v_lshl_add_u64 v[30:31], v[26:27], 0, v[16:17]
	v_mov_b32_e32 v19, v161
	v_lshl_add_u64 v[34:35], v[26:27], 0, v[18:19]
	global_load_dwordx2 v[26:27], v[28:29], off
	s_nop 0
	global_load_dwordx2 v[28:29], v[30:31], off
	s_nop 0
	global_load_dwordx2 v[30:31], v[34:35], off
